# LDS bank conflicts: gate-weight rows in LDS padded by 16 bytes (row stride 8208) so the 16 lanes writing one k no longer hit one bank; readers use the same stride
# baseline (speedup 1.0000x reference)
.LBB0_797:
	s_add_u32 s48, s80, 0xe00000
	s_addc_u32 s49, s81, 0
	s_cmp_lt_i32 s62, 9
	s_cselect_b64 s[0:1], -1, 0
	s_cmp_gt_i32 s63, 8
	s_cselect_b64 s[2:3], -1, 0
	s_and_b64 s[0:1], s[0:1], s[2:3]
	s_andn2_b64 vcc, exec, s[0:1]
	s_cbranch_vccnz .LBB0_875
	v_mov_b32_e32 v0, v212
	s_mov_b32 s0, 0x8000
	s_nop 0
	v_cmp_gt_i32_e32 vcc, s0, v0
	s_and_saveexec_b64 s[0:1], vcc
	s_cbranch_execz .LBB0_810
	s_waitcnt lgkmcnt(0)
	v_and_b32_e32 v9, 15, v0
	v_lshrrev_b32_e32 v1, 4, v0
	v_mul_u32_u24_e32 v8, 0x2010, v9
	v_lshl_add_u32 v10, v1, 2, v8
	v_mul_u32_u24_e32 v11, 0x8040, v1
	v_lshl_add_u32 v11, v9, 2, v11
	v_add_u32_e32 v11, 0x6000, v11
	s_mov_b64 s[2:3], s[70:71]
	global_load_dword v140, v11, s[2:3]
	s_add_u32 s2, s2, 0x100800
	s_addc_u32 s3, s3, 0
	global_load_dword v141, v11, s[2:3]
	s_add_u32 s2, s2, 0x100800
	s_addc_u32 s3, s3, 0
	global_load_dword v142, v11, s[2:3]
	s_add_u32 s2, s2, 0x100800
	s_addc_u32 s3, s3, 0
	global_load_dword v143, v11, s[2:3]
	s_add_u32 s2, s2, 0x100800
	s_addc_u32 s3, s3, 0
	global_load_dword v144, v11, s[2:3]
	s_add_u32 s2, s2, 0x100800
	s_addc_u32 s3, s3, 0
	global_load_dword v145, v11, s[2:3]
	s_add_u32 s2, s2, 0x100800
	s_addc_u32 s3, s3, 0
	global_load_dword v146, v11, s[2:3]
	s_add_u32 s2, s2, 0x100800
	s_addc_u32 s3, s3, 0
	global_load_dword v147, v11, s[2:3]
	s_add_u32 s2, s2, 0x100800
	s_addc_u32 s3, s3, 0
	global_load_dword v148, v11, s[2:3]
	s_add_u32 s2, s2, 0x100800
	s_addc_u32 s3, s3, 0
	global_load_dword v149, v11, s[2:3]
	s_add_u32 s2, s2, 0x100800
	s_addc_u32 s3, s3, 0
	global_load_dword v150, v11, s[2:3]
	s_add_u32 s2, s2, 0x100800
	s_addc_u32 s3, s3, 0
	global_load_dword v151, v11, s[2:3]
	s_add_u32 s2, s2, 0x100800
	s_addc_u32 s3, s3, 0
	global_load_dword v152, v11, s[2:3]
	s_add_u32 s2, s2, 0x100800
	s_addc_u32 s3, s3, 0
	global_load_dword v153, v11, s[2:3]
	s_add_u32 s2, s2, 0x100800
	s_addc_u32 s3, s3, 0
	global_load_dword v154, v11, s[2:3]
	s_add_u32 s2, s2, 0x100800
	s_addc_u32 s3, s3, 0
	global_load_dword v155, v11, s[2:3]
	s_add_u32 s2, s2, 0x100800
	s_addc_u32 s3, s3, 0
	global_load_dword v156, v11, s[2:3]
	s_add_u32 s2, s2, 0x100800
	s_addc_u32 s3, s3, 0
	global_load_dword v157, v11, s[2:3]
	s_add_u32 s2, s2, 0x100800
	s_addc_u32 s3, s3, 0
	global_load_dword v158, v11, s[2:3]
	s_add_u32 s2, s2, 0x100800
	s_addc_u32 s3, s3, 0
	global_load_dword v159, v11, s[2:3]
	s_add_u32 s2, s2, 0x100800
	s_addc_u32 s3, s3, 0
	global_load_dword v160, v11, s[2:3]
	s_add_u32 s2, s2, 0x100800
	s_addc_u32 s3, s3, 0
	global_load_dword v161, v11, s[2:3]
	s_add_u32 s2, s2, 0x100800
	s_addc_u32 s3, s3, 0
	global_load_dword v162, v11, s[2:3]
	s_add_u32 s2, s2, 0x100800
	s_addc_u32 s3, s3, 0
	global_load_dword v163, v11, s[2:3]
	s_add_u32 s2, s2, 0x100800
	s_addc_u32 s3, s3, 0
	global_load_dword v164, v11, s[2:3]
	s_add_u32 s2, s2, 0x100800
	s_addc_u32 s3, s3, 0
	global_load_dword v165, v11, s[2:3]
	s_add_u32 s2, s2, 0x100800
	s_addc_u32 s3, s3, 0
	global_load_dword v166, v11, s[2:3]
	s_add_u32 s2, s2, 0x100800
	s_addc_u32 s3, s3, 0
	global_load_dword v167, v11, s[2:3]
	s_add_u32 s2, s2, 0x100800
	s_addc_u32 s3, s3, 0
	global_load_dword v168, v11, s[2:3]
	s_add_u32 s2, s2, 0x100800
	s_addc_u32 s3, s3, 0
	global_load_dword v169, v11, s[2:3]
	s_add_u32 s2, s2, 0x100800
	s_addc_u32 s3, s3, 0
	global_load_dword v170, v11, s[2:3]
	s_add_u32 s2, s2, 0x100800
	s_addc_u32 s3, s3, 0
	global_load_dword v171, v11, s[2:3]
	s_add_u32 s2, s2, 0x100800
	s_addc_u32 s3, s3, 0
	global_load_dword v172, v11, s[2:3]
	s_add_u32 s2, s2, 0x100800
	s_addc_u32 s3, s3, 0
	global_load_dword v173, v11, s[2:3]
	s_add_u32 s2, s2, 0x100800
	s_addc_u32 s3, s3, 0
	global_load_dword v174, v11, s[2:3]
	s_add_u32 s2, s2, 0x100800
	s_addc_u32 s3, s3, 0
	global_load_dword v175, v11, s[2:3]
	s_add_u32 s2, s2, 0x100800
	s_addc_u32 s3, s3, 0
	global_load_dword v176, v11, s[2:3]
	s_add_u32 s2, s2, 0x100800
	s_addc_u32 s3, s3, 0
	global_load_dword v177, v11, s[2:3]
	s_add_u32 s2, s2, 0x100800
	s_addc_u32 s3, s3, 0
	global_load_dword v178, v11, s[2:3]
	s_add_u32 s2, s2, 0x100800
	s_addc_u32 s3, s3, 0
	global_load_dword v179, v11, s[2:3]
	s_add_u32 s2, s2, 0x100800
	s_addc_u32 s3, s3, 0
	global_load_dword v180, v11, s[2:3]
	s_add_u32 s2, s2, 0x100800
	s_addc_u32 s3, s3, 0
	global_load_dword v181, v11, s[2:3]
	s_add_u32 s2, s2, 0x100800
	s_addc_u32 s3, s3, 0
	global_load_dword v182, v11, s[2:3]
	s_add_u32 s2, s2, 0x100800
	s_addc_u32 s3, s3, 0
	global_load_dword v183, v11, s[2:3]
	s_add_u32 s2, s2, 0x100800
	s_addc_u32 s3, s3, 0
	global_load_dword v184, v11, s[2:3]
	s_add_u32 s2, s2, 0x100800
	s_addc_u32 s3, s3, 0
	global_load_dword v185, v11, s[2:3]
	s_add_u32 s2, s2, 0x100800
	s_addc_u32 s3, s3, 0
	global_load_dword v186, v11, s[2:3]
	s_add_u32 s2, s2, 0x100800
	s_addc_u32 s3, s3, 0
	global_load_dword v187, v11, s[2:3]
	s_add_u32 s2, s2, 0x100800
	s_addc_u32 s3, s3, 0
	global_load_dword v188, v11, s[2:3]
	s_add_u32 s2, s2, 0x100800
	s_addc_u32 s3, s3, 0
	global_load_dword v189, v11, s[2:3]
	s_add_u32 s2, s2, 0x100800
	s_addc_u32 s3, s3, 0
	global_load_dword v190, v11, s[2:3]
	s_add_u32 s2, s2, 0x100800
	s_addc_u32 s3, s3, 0
	global_load_dword v191, v11, s[2:3]
	s_add_u32 s2, s2, 0x100800
	s_addc_u32 s3, s3, 0
	global_load_dword v192, v11, s[2:3]
	s_add_u32 s2, s2, 0x100800
	s_addc_u32 s3, s3, 0
	global_load_dword v193, v11, s[2:3]
	s_add_u32 s2, s2, 0x100800
	s_addc_u32 s3, s3, 0
	global_load_dword v194, v11, s[2:3]
	s_add_u32 s2, s2, 0x100800
	s_addc_u32 s3, s3, 0
	global_load_dword v195, v11, s[2:3]
	s_add_u32 s2, s2, 0x100800
	s_addc_u32 s3, s3, 0
	global_load_dword v196, v11, s[2:3]
	s_add_u32 s2, s2, 0x100800
	s_addc_u32 s3, s3, 0
	global_load_dword v197, v11, s[2:3]
	s_add_u32 s2, s2, 0x100800
	s_addc_u32 s3, s3, 0
	global_load_dword v198, v11, s[2:3]
	s_add_u32 s2, s2, 0x100800
	s_addc_u32 s3, s3, 0
	global_load_dword v199, v11, s[2:3]
	s_add_u32 s2, s2, 0x100800
	s_addc_u32 s3, s3, 0
	global_load_dword v200, v11, s[2:3]
	s_add_u32 s2, s2, 0x100800
	s_addc_u32 s3, s3, 0
	global_load_dword v201, v11, s[2:3]
	s_add_u32 s2, s2, 0x100800
	s_addc_u32 s3, s3, 0
	global_load_dword v202, v11, s[2:3]
	s_add_u32 s2, s2, 0x100800
	s_addc_u32 s3, s3, 0
	global_load_dword v203, v11, s[2:3]
	s_waitcnt vmcnt(48)
	ds_write_b32 v10, v140
	ds_write_b32 v10, v141 offset:128
	ds_write_b32 v10, v142 offset:256
	ds_write_b32 v10, v143 offset:384
	ds_write_b32 v10, v144 offset:512
	ds_write_b32 v10, v145 offset:640
	ds_write_b32 v10, v146 offset:768
	ds_write_b32 v10, v147 offset:896
	ds_write_b32 v10, v148 offset:1024
	ds_write_b32 v10, v149 offset:1152
	ds_write_b32 v10, v150 offset:1280
	ds_write_b32 v10, v151 offset:1408
	ds_write_b32 v10, v152 offset:1536
	ds_write_b32 v10, v153 offset:1664
	ds_write_b32 v10, v154 offset:1792
	ds_write_b32 v10, v155 offset:1920
	s_waitcnt vmcnt(32)
	ds_write_b32 v10, v156 offset:2048
	ds_write_b32 v10, v157 offset:2176
	ds_write_b32 v10, v158 offset:2304
	ds_write_b32 v10, v159 offset:2432
	ds_write_b32 v10, v160 offset:2560
	ds_write_b32 v10, v161 offset:2688
	ds_write_b32 v10, v162 offset:2816
	ds_write_b32 v10, v163 offset:2944
	ds_write_b32 v10, v164 offset:3072
	ds_write_b32 v10, v165 offset:3200
	ds_write_b32 v10, v166 offset:3328
	ds_write_b32 v10, v167 offset:3456
	ds_write_b32 v10, v168 offset:3584
	ds_write_b32 v10, v169 offset:3712
	ds_write_b32 v10, v170 offset:3840
	ds_write_b32 v10, v171 offset:3968
	s_waitcnt vmcnt(16)
	ds_write_b32 v10, v172 offset:4096
	ds_write_b32 v10, v173 offset:4224
	ds_write_b32 v10, v174 offset:4352
	ds_write_b32 v10, v175 offset:4480
	ds_write_b32 v10, v176 offset:4608
	ds_write_b32 v10, v177 offset:4736
	ds_write_b32 v10, v178 offset:4864
	ds_write_b32 v10, v179 offset:4992
	ds_write_b32 v10, v180 offset:5120
	ds_write_b32 v10, v181 offset:5248
	ds_write_b32 v10, v182 offset:5376
	ds_write_b32 v10, v183 offset:5504
	ds_write_b32 v10, v184 offset:5632
	ds_write_b32 v10, v185 offset:5760
	ds_write_b32 v10, v186 offset:5888
	ds_write_b32 v10, v187 offset:6016
	s_waitcnt vmcnt(0)
	ds_write_b32 v10, v188 offset:6144
	ds_write_b32 v10, v189 offset:6272
	ds_write_b32 v10, v190 offset:6400
	ds_write_b32 v10, v191 offset:6528
	ds_write_b32 v10, v192 offset:6656
	ds_write_b32 v10, v193 offset:6784
	ds_write_b32 v10, v194 offset:6912
	ds_write_b32 v10, v195 offset:7040
	ds_write_b32 v10, v196 offset:7168
	ds_write_b32 v10, v197 offset:7296
	ds_write_b32 v10, v198 offset:7424
	ds_write_b32 v10, v199 offset:7552
	ds_write_b32 v10, v200 offset:7680
	ds_write_b32 v10, v201 offset:7808
	ds_write_b32 v10, v202 offset:7936
	ds_write_b32 v10, v203 offset:8064
.LBB0_810:
	s_or_b64 exec, exec, s[0:1]
	s_cmpk_gt_i32 s84, 0xff
	s_waitcnt vmcnt(0) lgkmcnt(0)
	s_barrier
	s_cbranch_scc1 .LBB0_821
	v_and_b32_e32 v50, 63, v0
	v_mbcnt_lo_u32_b32 v0, -1, 0
	v_mbcnt_hi_u32_b32 v2, -1, v0
	v_and_b32_e32 v3, 64, v2
	v_add_u32_e32 v0, 64, v3
	v_xor_b32_e32 v1, 1, v2
	v_cmp_lt_i32_e32 vcc, v1, v0
	v_mov_b32_e32 v29, 0
	v_readlane_b32 s52, v255, 7
	v_cndmask_b32_e32 v1, v2, v1, vcc
	v_lshlrev_b32_e32 v51, 2, v1
	v_xor_b32_e32 v1, 2, v2
	v_cmp_lt_i32_e32 vcc, v1, v0
	v_lshlrev_b32_e32 v28, 4, v50
	s_add_i32 s4, 0, 0x21000
	v_cndmask_b32_e32 v1, v2, v1, vcc
	v_lshlrev_b32_e32 v52, 2, v1
	v_xor_b32_e32 v1, 4, v2
	v_cmp_lt_i32_e32 vcc, v1, v0
	v_readlane_b32 s56, v255, 11
	v_readlane_b32 s57, v255, 12
	v_cndmask_b32_e32 v1, v2, v1, vcc
	v_lshlrev_b32_e32 v53, 2, v1
	v_xor_b32_e32 v1, 8, v2
	v_cmp_lt_i32_e32 vcc, v1, v0
	s_mov_b64 s[0:1], 0x4000
	s_lshl_b32 s17, s90, 3
	v_cndmask_b32_e32 v1, v2, v1, vcc
	v_lshlrev_b32_e32 v54, 2, v1
	v_xor_b32_e32 v1, 16, v2
	v_cmp_lt_i32_e32 vcc, v1, v0
	v_lshl_add_u64 v[30:31], s[78:79], 0, v[28:29]
	v_add_u32_e32 v57, 0, v28
	v_cndmask_b32_e32 v1, v2, v1, vcc
	v_lshlrev_b32_e32 v55, 2, v1
	v_xor_b32_e32 v1, 32, v2
	v_cmp_lt_i32_e32 vcc, v1, v0
	v_cmp_gt_u32_e64 s[2:3], 16, v50
	v_cmp_gt_u32_e64 s[6:7], 2, v50
	v_cndmask_b32_e32 v0, v2, v1, vcc
	v_lshlrev_b32_e32 v56, 2, v0
	v_lshlrev_b32_e32 v0, 3, v50
	v_mov_b32_e32 v1, v29
	v_lshl_add_u64 v[32:33], s[50:51], 0, v[0:1]
	v_lshlrev_b32_e32 v0, 2, v50
	v_add_u32_e32 v58, s4, v0
	v_lshl_add_u64 v[34:35], s[72:73], 0, v[0:1]
	v_lshl_add_u64 v[0:1], s[56:57], 0, v[28:29]
	v_lshl_add_u64 v[36:37], v[0:1], 0, s[0:1]
	s_mov_b64 s[0:1], 0x5000
	v_lshl_add_u64 v[38:39], v[0:1], 0, s[0:1]
	s_mov_b64 s[0:1], 0x5400
	v_lshl_add_u64 v[40:41], v[0:1], 0, s[0:1]
	s_mov_b64 s[0:1], 0x5800
	v_lshl_add_u64 v[42:43], v[0:1], 0, s[0:1]
	s_mov_b64 s[0:1], 0x5c00
	v_lshl_add_u64 v[44:45], v[0:1], 0, s[0:1]
	v_add_u32_e32 v0, -1, v2
	v_cmp_lt_i32_e32 vcc, v0, v3
	s_lshl_b32 s0, s90, 2
	s_add_i32 s0, s0, s4
	v_cndmask_b32_e32 v0, v0, v2, vcc
	v_lshlrev_b32_e32 v59, 2, v0
	v_add_u32_e32 v0, -2, v2
	v_cmp_lt_i32_e32 vcc, v0, v3
	v_lshl_add_u32 v28, v50, 6, s0
	v_cmp_eq_u32_e64 s[4:5], 0, v50
	v_cndmask_b32_e32 v0, v0, v2, vcc
	v_lshlrev_b32_e32 v60, 2, v0
	v_add_u32_e32 v0, -4, v2
	v_cmp_lt_i32_e32 vcc, v0, v3
	v_cmp_gt_u32_e64 s[8:9], 4, v50
	v_cmp_gt_u32_e64 s[10:11], 8, v50
	v_cndmask_b32_e32 v0, v0, v2, vcc
	v_lshlrev_b32_e32 v61, 2, v0
	v_add_u32_e32 v0, -8, v2
	v_cmp_lt_i32_e32 vcc, v0, v3
	v_cmp_gt_u32_e64 s[12:13], 32, v50
	v_cmp_eq_u32_e64 s[14:15], 63, v50
	v_cndmask_b32_e32 v0, v0, v2, vcc
	v_lshlrev_b32_e32 v62, 2, v0
	v_add_u32_e32 v0, -16, v2
	v_cmp_lt_i32_e32 vcc, v0, v3
	v_mul_u32_u24_e32 v65, 0x2010, v50
	s_movk_i32 s18, 0x1000
	v_cndmask_b32_e32 v0, v0, v2, vcc
	v_lshlrev_b32_e32 v63, 2, v0
	v_subrev_u32_e32 v0, 32, v2
	v_cmp_lt_i32_e32 vcc, v0, v3
	v_mov_b32_e32 v66, 0x358637bd
	s_mov_b32 s19, 0xf800000
	v_cndmask_b32_e32 v0, v0, v2, vcc
	v_lshlrev_b32_e32 v64, 2, v0
	v_mov_b32_e32 v67, 0x260
	s_mov_b32 s20, 0xbfb8aa3b
	s_mov_b32 s21, 0xb2a5705f
	s_mov_b32 s22, 0x42ce8ed0
	s_mov_b32 s23, 0xc2b17218
	s_mov_b32 s24, 0x7f800000
	s_mov_b32 s25, 0x3f2aaaab
	v_mov_b32_e32 v68, 0x3ecc95a3
	s_mov_b32 s26, 0x3f317218
	s_mov_b32 s27, 0x33800000
	v_mov_b32_e32 v69, 0x7f800000
	s_mov_b32 s28, s84
	v_readlane_b32 s53, v255, 8
	v_readlane_b32 s54, v255, 9
	v_readlane_b32 s55, v255, 10
	v_readlane_b32 s58, v255, 13
	v_readlane_b32 s59, v255, 14
	v_readlane_b32 s60, v255, 15
	v_readlane_b32 s61, v255, 16
	v_readlane_b32 s62, v255, 17
	v_readlane_b32 s63, v255, 18
	v_readlane_b32 s64, v255, 19
	v_readlane_b32 s65, v255, 20
	v_readlane_b32 s66, v255, 21
	v_readlane_b32 s67, v255, 22
	s_branch .LBB0_813

.Lmy_p8_nopf:
.LBB0_816:
	v_add_u32_e32 v71, s0, v57
	ds_read_b128 v[72:75], v71
	ds_read_b128 v[76:79], v71 offset:1024
	ds_read_b128 v[80:83], v71 offset:2048
	ds_read_b128 v[84:87], v71 offset:3072
	ds_read_b128 v[88:91], v71 offset:4096
	ds_read_b128 v[92:95], v71 offset:5120
	ds_read_b128 v[96:99], v71 offset:6144
	ds_read_b128 v[100:103], v71 offset:7168
	s_waitcnt lgkmcnt(6)
	v_mov_b32_e32 v105, v76
	v_mov_b32_e32 v76, v73
	v_mov_b32_e32 v73, v78
	v_mov_b32_e32 v78, v75
	v_mov_b32_e32 v104, v72
	v_mov_b32_e32 v72, v74
	s_waitcnt lgkmcnt(5)
	v_pk_mul_f32 v[74:75], v[26:27], v[82:83]
	v_pk_mul_f32 v[80:81], v[24:25], v[80:81]
	v_pk_mul_f32 v[76:77], v[10:11], v[76:77]
	v_pk_mul_f32 v[78:79], v[8:9], v[78:79]
	s_waitcnt lgkmcnt(0)
	v_mul_f32_e32 v108, v46, v102
	v_mul_f32_e32 v109, v47, v103
	v_pk_mov_b32 v[102:103], v[80:81], v[74:75] op_sel:[1,0]
	v_mov_b32_e32 v81, v75
	v_pk_fma_f32 v[76:77], v[0:1], v[104:105], v[76:77]
	v_pk_fma_f32 v[72:73], v[2:3], v[72:73], v[78:79]
	v_mul_f32_e32 v83, v6, v88
	v_mul_f32_e32 v82, v17, v85
	v_mul_f32_e32 v88, v19, v87
	v_pk_add_f32 v[78:79], v[102:103], v[80:81]
	v_pk_add_f32 v[72:73], v[76:77], v[72:73]
	v_mul_f32_e32 v71, v7, v89
	v_mul_f32_e32 v106, v4, v90
	v_mul_f32_e32 v107, v5, v91
	v_pk_fma_f32 v[74:75], v[16:17], v[84:85], v[82:83] op_sel_hi:[1,1,0]
	v_pk_fma_f32 v[84:85], v[18:19], v[86:87], v[88:89] op_sel_hi:[1,1,0]
	v_pk_add_f32 v[76:77], v[78:79], v[78:79] op_sel:[0,1] op_sel_hi:[1,0]
	v_add_f32_e32 v72, 0, v72
	v_pk_mul_f32 v[90:91], v[22:23], v[94:95]
	v_pk_mul_f32 v[92:93], v[20:21], v[92:93]
	v_mov_b32_e32 v75, v106
	v_mov_b32_e32 v85, v107
	v_mov_b32_e32 v77, v71
	v_add_f32_e32 v82, v72, v73
	v_pk_mov_b32 v[86:87], v[92:93], v[90:91] op_sel:[1,0]
	v_mov_b32_e32 v93, v91
	v_pk_add_f32 v[74:75], v[74:75], v[84:85]
	v_pk_add_f32 v[72:73], v[82:83], v[76:77]
	v_mul_f32_e32 v95, v48, v100
	v_mul_f32_e32 v101, v49, v101
	v_mul_f32_e32 v94, v13, v97
	v_mul_f32_e32 v100, v15, v99
	v_pk_add_f32 v[80:81], v[86:87], v[92:93]
	v_pk_add_f32 v[72:73], v[72:73], v[74:75]
	v_pk_fma_f32 v[88:89], v[12:13], v[96:97], v[94:95] op_sel_hi:[1,1,0]
	v_pk_fma_f32 v[90:91], v[14:15], v[98:99], v[100:101] op_sel_hi:[1,1,0]
	v_pk_add_f32 v[78:79], v[80:81], v[80:81] op_sel:[0,1] op_sel_hi:[1,0]
	v_pk_add_f32 v[72:73], v[72:73], v[72:73] op_sel:[0,1] op_sel_hi:[1,0]
	v_mov_b32_e32 v89, v108
	v_mov_b32_e32 v91, v109
	v_mov_b32_e32 v79, v101
	v_mov_b32_e32 v73, v95
	v_pk_add_f32 v[80:81], v[88:89], v[90:91]
	v_pk_add_f32 v[72:73], v[72:73], v[78:79]
	v_cmp_eq_u32_e32 vcc, s0, v65
	v_pk_add_f32 v[72:73], v[72:73], v[80:81]
	s_addk_i32 s0, 0x2010
	v_add_f32_e32 v71, v72, v73
	s_cmp_lg_u32 s0, 0x20100
	s_waitcnt lgkmcnt(0)
	s_nop 1
	v_add_f32_dpp v71, v71, v71 quad_perm:[1,0,3,2] row_mask:0xf bank_mask:0xf
	s_waitcnt lgkmcnt(0)
	s_nop 1
	v_add_f32_dpp v71, v71, v71 quad_perm:[2,3,0,1] row_mask:0xf bank_mask:0xf
	s_waitcnt lgkmcnt(0)
	s_nop 1
	v_add_f32_dpp v71, v71, v71 row_half_mirror row_mask:0xf bank_mask:0xf
	s_waitcnt lgkmcnt(0)
	s_nop 1
	v_add_f32_dpp v71, v71, v71 row_mirror row_mask:0xf bank_mask:0xf
	s_waitcnt lgkmcnt(0)
	v_mov_b32_e32 v72, v71
	s_nop 1
	v_permlane16_swap_b32_e32 v71, v72
	v_add_f32_e32 v71, v71, v72
	s_waitcnt lgkmcnt(0)
	v_mov_b32_e32 v72, v71
	s_nop 1
	v_permlane32_swap_b32_e32 v71, v72
	v_add_f32_e32 v71, v71, v72
	v_cndmask_b32_e32 v70, v70, v71, vcc
	s_cbranch_scc1 .LBB0_816
	s_and_saveexec_b64 s[0:1], s[2:3]
	s_cbranch_execz .LBB0_814
	v_lshl_add_u32 v1, s31, 6, v58
	v_add_f32_e32 v0, v70, v204
	ds_write_b32 v1, v0
	s_branch .LBB0_814
